# S5 prompt full pass: the chunk's 16 BU reads and 4 H-fragment reads issued together (one LDS wait each instead of per step)
# speedup vs baseline: 1.0059x; 1.0059x over previous
.LBB0_722:
	v_fmamk_f32 v3, v64, 0x3a000000, v203
	v_rsq_f32_e32 v119, v3
	v_fmamk_f32 v3, v65, 0x3a000000, v203
	v_rsq_f32_e32 v120, v3
	v_fmamk_f32 v3, v66, 0x3a000000, v203
	v_rsq_f32_e32 v121, v3
	v_fmamk_f32 v3, v67, 0x3a000000, v203
	v_rsq_f32_e32 v3, v3
	v_mfma_f32_16x16x32_bf16 v[64:67], v[60:63], v[4:7], 0
	v_lshl_add_u64 v[106:107], v[106:107], 0, 64
	s_nop 6
	v_mul_f32_e32 v122, v119, v64
	v_mul_f32_e32 v123, v120, v65
	v_mul_f32_e32 v124, v121, v66
	v_mul_f32_e32 v125, v3, v67
	v_mfma_f32_16x16x32_bf16 v[64:67], v[60:63], v[8:11], 0
	s_nop 7
	v_mul_f32_e32 v64, v119, v64
	ds_write2_b32 v73, v122, v64 offset1:16
	v_mul_f32_e32 v64, v120, v65
	ds_write2_b32 v73, v123, v64 offset0:132 offset1:148
	v_mul_f32_e32 v64, v121, v66
	v_add_u32_e32 v122, 0x400, v73
	ds_write2_b32 v122, v124, v64 offset0:8 offset1:24
	v_mul_f32_e32 v64, v3, v67
	ds_write2_b32 v122, v125, v64 offset0:140 offset1:156
	v_mfma_f32_16x16x32_bf16 v[64:67], v[60:63], v[12:15], 0
	s_nop 7
	v_mul_f32_e32 v123, v119, v64
	v_mul_f32_e32 v124, v120, v65
	v_mul_f32_e32 v125, v121, v66
	v_mul_f32_e32 v126, v3, v67
	v_mfma_f32_16x16x32_bf16 v[64:67], v[60:63], v[16:19], 0
	s_nop 7
	v_mul_f32_e32 v64, v119, v64
	ds_write2_b32 v73, v123, v64 offset0:32 offset1:48
	v_mul_f32_e32 v64, v120, v65
	ds_write2_b32 v73, v124, v64 offset0:164 offset1:180
	v_mul_f32_e32 v64, v121, v66
	ds_write2_b32 v122, v125, v64 offset0:40 offset1:56
	v_mul_f32_e32 v64, v3, v67
	ds_write2_b32 v122, v126, v64 offset0:172 offset1:188
	v_mfma_f32_16x16x32_bf16 v[64:67], v[60:63], v[20:23], 0
	s_nop 7
	v_mul_f32_e32 v123, v119, v64
	v_mul_f32_e32 v124, v120, v65
	v_mul_f32_e32 v125, v121, v66
	v_mul_f32_e32 v126, v3, v67
	v_mfma_f32_16x16x32_bf16 v[64:67], v[60:63], v[24:27], 0
	s_nop 7
	v_mul_f32_e32 v64, v119, v64
	ds_write2_b32 v73, v123, v64 offset0:64 offset1:80
	v_mul_f32_e32 v64, v120, v65
	ds_write2_b32 v73, v124, v64 offset0:196 offset1:212
	v_mul_f32_e32 v64, v121, v66
	ds_write2_b32 v122, v125, v64 offset0:72 offset1:88
	v_mul_f32_e32 v64, v3, v67
	ds_write2_b32 v122, v126, v64 offset0:204 offset1:220
	v_mfma_f32_16x16x32_bf16 v[64:67], v[60:63], v[28:31], 0
	v_mfma_f32_16x16x32_bf16 v[60:63], v[60:63], v[32:35], 0
	s_nop 6
	v_mul_f32_e32 v64, v119, v64
	v_mul_f32_e32 v60, v119, v60
	v_mul_f32_e32 v65, v120, v65
	ds_write2_b32 v73, v64, v60 offset0:96 offset1:112
	v_mul_f32_e32 v60, v120, v61
	v_mul_f32_e32 v66, v121, v66
	ds_write2_b32 v73, v65, v60 offset0:228 offset1:244
	v_mul_f32_e32 v60, v121, v62
	v_mul_f32_e32 v67, v3, v67
	ds_write2_b32 v122, v66, v60 offset0:104 offset1:120
	v_mul_f32_e32 v60, v3, v63
	ds_write2_b32 v122, v67, v60 offset0:236 offset1:252
	s_waitcnt lgkmcnt(0)
	v_add_u32_e32 v62, s42, v69
	ds_read_b64 v[130:131], v62
	ds_read_b64 v[132:133], v62 offset:528
	ds_read_b64 v[134:135], v62 offset:1056
	ds_read_b64 v[136:137], v62 offset:1584
	ds_read_b64 v[138:139], v62 offset:2112
	ds_read_b64 v[140:141], v62 offset:2640
	ds_read_b64 v[142:143], v62 offset:3168
	ds_read_b64 v[144:145], v62 offset:3696
	ds_read_b64 v[146:147], v62 offset:4224
	ds_read_b64 v[148:149], v62 offset:4752
	ds_read_b64 v[150:151], v62 offset:5280
	ds_read_b64 v[152:153], v62 offset:5808
	ds_read_b64 v[154:155], v62 offset:6336
	ds_read_b64 v[156:157], v62 offset:6864
	ds_read_b64 v[158:159], v62 offset:7392
	ds_read_b64 v[160:161], v62 offset:7920
	s_waitcnt lgkmcnt(0)
	v_fma_f32 v60, -v99, v115, v130
	v_add_u32_e32 v122, v113, v76
	v_fma_f32 v63, v98, v116, v60
	v_fma_f32 v60, v99, v116, v131
	v_mul_f32_e32 v3, v114, v3
	v_fma_f32 v64, v98, v115, v60
	s_nop 0
	v_cvt_pk_bf16_f32 v65, v63, v64
	v_fma_f32 v60, -v99, v64, v132
	ds_write_b32 v112, v65 offset:8448
	v_fma_f32 v65, v98, v63, v60
	v_fma_f32 v60, v99, v63, v133
	s_nop 0
	v_fma_f32 v63, v98, v64, v60
	s_nop 0
	v_cvt_pk_bf16_f32 v64, v65, v63
	v_fma_f32 v60, -v99, v63, v134
	ds_write_b32 v112, v64 offset:8720
	v_fma_f32 v64, v98, v65, v60
	v_fma_f32 v60, v99, v65, v135
	s_nop 0
	v_fma_f32 v63, v98, v63, v60
	s_nop 0
	v_cvt_pk_bf16_f32 v65, v64, v63
	v_fma_f32 v60, -v99, v63, v136
	ds_write_b32 v112, v65 offset:8992
	v_fma_f32 v65, v98, v64, v60
	v_fma_f32 v60, v99, v64, v137
	s_nop 0
	v_fma_f32 v63, v98, v63, v60
	s_nop 0
	v_cvt_pk_bf16_f32 v64, v65, v63
	v_fma_f32 v60, -v99, v63, v138
	ds_write_b32 v112, v64 offset:9264
	v_fma_f32 v64, v98, v65, v60
	v_fma_f32 v60, v99, v65, v139
	s_nop 0
	v_fma_f32 v63, v98, v63, v60
	s_nop 0
	v_cvt_pk_bf16_f32 v65, v64, v63
	v_fma_f32 v60, -v99, v63, v140
	ds_write_b32 v112, v65 offset:9536
	v_fma_f32 v65, v98, v64, v60
	v_fma_f32 v60, v99, v64, v141
	s_nop 0
	v_fma_f32 v63, v98, v63, v60
	s_nop 0
	v_cvt_pk_bf16_f32 v64, v65, v63
	v_fma_f32 v60, -v99, v63, v142
	ds_write_b32 v112, v64 offset:9808
	v_fma_f32 v64, v98, v65, v60
	v_fma_f32 v60, v99, v65, v143
	s_nop 0
	v_fma_f32 v63, v98, v63, v60
	s_nop 0
	v_cvt_pk_bf16_f32 v65, v64, v63
	v_fma_f32 v60, -v99, v63, v144
	ds_write_b32 v112, v65 offset:10080
	v_fma_f32 v65, v98, v64, v60
	v_fma_f32 v60, v99, v64, v145
	s_nop 0
	v_fma_f32 v63, v98, v63, v60
	s_nop 0
	v_cvt_pk_bf16_f32 v64, v65, v63
	v_fma_f32 v60, -v99, v63, v146
	ds_write_b32 v112, v64 offset:10352
	v_fma_f32 v64, v98, v65, v60
	v_fma_f32 v60, v99, v65, v147
	s_nop 0
	v_fma_f32 v63, v98, v63, v60
	s_nop 0
	v_cvt_pk_bf16_f32 v65, v64, v63
	v_fma_f32 v60, -v99, v63, v148
	ds_write_b32 v112, v65 offset:10624
	v_fma_f32 v65, v98, v64, v60
	v_fma_f32 v60, v99, v64, v149
	s_nop 0
	v_fma_f32 v63, v98, v63, v60
	s_nop 0
	v_cvt_pk_bf16_f32 v64, v65, v63
	v_fma_f32 v60, -v99, v63, v150
	ds_write_b32 v112, v64 offset:10896
	v_fma_f32 v64, v98, v65, v60
	v_fma_f32 v60, v99, v65, v151
	s_nop 0
	v_fma_f32 v63, v98, v63, v60
	s_nop 0
	v_cvt_pk_bf16_f32 v65, v64, v63
	v_fma_f32 v60, -v99, v63, v152
	ds_write_b32 v112, v65 offset:11168
	v_fma_f32 v65, v98, v64, v60
	v_fma_f32 v60, v99, v64, v153
	s_nop 0
	v_fma_f32 v63, v98, v63, v60
	s_nop 0
	v_cvt_pk_bf16_f32 v64, v65, v63
	v_fma_f32 v60, -v99, v63, v154
	ds_write_b32 v112, v64 offset:11440
	v_fma_f32 v64, v98, v65, v60
	v_fma_f32 v60, v99, v65, v155
	s_nop 0
	v_fma_f32 v63, v98, v63, v60
	s_nop 0
	v_cvt_pk_bf16_f32 v65, v64, v63
	v_fma_f32 v60, -v99, v63, v156
	ds_write_b32 v112, v65 offset:11712
	v_fma_f32 v65, v98, v64, v60
	v_fma_f32 v60, v99, v64, v157
	s_nop 0
	v_fma_f32 v63, v98, v63, v60
	s_nop 0
	v_cvt_pk_bf16_f32 v64, v65, v63
	v_fma_f32 v60, -v99, v63, v158
	ds_write_b32 v112, v64 offset:11984
	v_fma_f32 v64, v98, v65, v60
	v_fma_f32 v60, v99, v65, v159
	s_nop 0
	v_fma_f32 v63, v98, v63, v60
	s_nop 0
	v_cvt_pk_bf16_f32 v65, v64, v63
	v_fma_f32 v60, -v99, v63, v160
	ds_write_b32 v112, v65 offset:12256
	v_fma_f32 v116, v98, v64, v60
	v_fma_f32 v60, v99, v64, v161
	s_nop 0
	v_fma_f32 v115, v98, v63, v60
	s_nop 0
	v_cvt_pk_bf16_f32 v60, v116, v115
	ds_write_b32 v112, v60 offset:12528
	s_waitcnt lgkmcnt(0)
	ds_read_b128 v[60:63], v122 offset:8448
	ds_read_b128 v[64:67], v122 offset:8512
	ds_read_b128 v[162:165], v122 offset:8576
	ds_read_b128 v[166:169], v122 offset:8640
	v_lshlrev_b32_e32 v122, 16, v117
	s_waitcnt lgkmcnt(0)
	v_mfma_f32_16x16x32_bf16 v[60:63], v[60:63], v[36:39], 0
	v_mfma_f32_16x16x32_bf16 v[60:63], v[64:67], v[40:43], v[60:63]
	v_mfma_f32_16x16x32_bf16 v[60:63], v[162:165], v[44:47], v[60:63]
	v_mfma_f32_16x16x32_bf16 v[60:63], v[166:169], v[48:51], v[60:63]
	v_mul_f32_e32 v64, v114, v119
	v_and_b32_e32 v67, 0xffff0000, v117
	v_lshlrev_b32_e32 v117, 16, v118
	s_nop 4
	v_fma_f32 v60, v64, v122, v60
	v_mul_f32_e32 v64, 0x3d372713, v60
	v_mul_f32_e32 v64, v60, v64
	v_fma_f32 v64, v60, v64, v60
	v_mul_f32_e32 v64, 0xbfcc422a, v64
	v_mul_f32_e32 v64, 0x3fb8aa3b, v64
	v_exp_f32_e32 v64, v64
	v_and_b32_e32 v118, 0xffff0000, v118
	v_fmac_f32_e32 v63, v3, v118
	v_mul_f32_e32 v3, 0x3d372713, v63
	v_add_f32_e32 v64, 1.0, v64
	v_div_scale_f32 v65, s[2:3], v64, v64, v60
	v_rcp_f32_e32 v66, v65
	v_mul_f32_e32 v3, v63, v3
	v_fma_f32 v3, v63, v3, v63
	v_mul_f32_e32 v3, 0xbfcc422a, v3
	v_fma_f32 v119, -v65, v66, 1.0
	v_fmac_f32_e32 v66, v119, v66
	v_div_scale_f32 v119, vcc, v60, v64, v60
	v_mul_f32_e32 v122, v119, v66
	v_fma_f32 v123, -v65, v122, v119
	v_fmac_f32_e32 v122, v123, v66
	v_fma_f32 v65, -v65, v122, v119
	v_div_fmas_f32 v65, v65, v66, v122
	v_div_fixup_f32 v60, v65, v64, v60
	v_bfe_u32 v64, v60, 16, 1
	v_add3_u32 v66, v60, v64, s85
	v_mul_f32_e32 v60, v114, v120
	v_fma_f32 v67, v60, v67, v61
	v_mul_f32_e32 v60, 0x3d372713, v67
	v_mul_f32_e32 v60, v67, v60
	v_fma_f32 v60, v67, v60, v67
	v_mul_f32_e32 v60, 0xbfcc422a, v60
	v_mul_f32_e32 v60, 0x3fb8aa3b, v60
	v_exp_f32_e32 v65, v60
	v_lshl_add_u64 v[60:61], v[102:103], 0, s[30:31]
	v_add_co_u32_e32 v64, vcc, s33, v60
	v_add_f32_e32 v119, 1.0, v65
	v_div_scale_f32 v120, s[2:3], v119, v119, v67
	v_rcp_f32_e32 v122, v120
	v_addc_co_u32_e32 v65, vcc, 0, v61, vcc
	global_store_short_d16_hi v[64:65], v66, off offset:-4096
	v_fma_f32 v66, -v120, v122, 1.0
	v_fmac_f32_e32 v122, v66, v122
	v_div_scale_f32 v66, vcc, v67, v119, v67
	v_mul_f32_e32 v123, v66, v122
	v_fma_f32 v124, -v120, v123, v66
	v_fmac_f32_e32 v123, v124, v122
	v_fma_f32 v66, -v120, v123, v66
	v_mul_f32_e32 v120, v114, v121
	v_fma_f32 v62, v120, v117, v62
	v_mul_f32_e32 v117, 0x3d372713, v62
	v_mul_f32_e32 v117, v62, v117
	v_fma_f32 v117, v62, v117, v62
	v_mul_f32_e32 v117, 0xbfcc422a, v117
	v_mul_f32_e32 v117, 0x3fb8aa3b, v117
	v_exp_f32_e32 v117, v117
	v_div_fmas_f32 v66, v66, v122, v123
	v_div_fixup_f32 v66, v66, v119, v67
	v_bfe_u32 v120, v66, 16, 1
	v_add_f32_e32 v67, 1.0, v117
	v_div_scale_f32 v117, s[2:3], v67, v67, v62
	v_rcp_f32_e32 v119, v117
	v_add3_u32 v66, v66, v120, s85
	global_store_short_d16_hi v[64:65], v66, off
	v_mul_f32_e32 v3, 0x3fb8aa3b, v3
	v_fma_f32 v64, -v117, v119, 1.0
	v_fmac_f32_e32 v119, v64, v119
	v_div_scale_f32 v64, vcc, v62, v67, v62
	v_mul_f32_e32 v65, v64, v119
	v_fma_f32 v66, -v117, v65, v64
	v_fmac_f32_e32 v65, v66, v119
	v_exp_f32_e32 v3, v3
	v_fma_f32 v64, -v117, v65, v64
	v_div_fmas_f32 v64, v64, v119, v65
	v_div_fixup_f32 v62, v64, v67, v62
	v_bfe_u32 v64, v62, 16, 1
	v_add_f32_e32 v3, 1.0, v3
	v_add3_u32 v62, v62, v64, s85
	v_div_scale_f32 v64, s[2:3], v3, v3, v63
	v_rcp_f32_e32 v65, v64
	v_add_co_u32_e32 v60, vcc, s46, v60
	s_add_u32 s30, s30, 0x10000
	s_nop 0
	v_addc_co_u32_e32 v61, vcc, 0, v61, vcc
	global_store_short_d16_hi v[60:61], v62, off offset:-4096
	v_fma_f32 v62, -v64, v65, 1.0
	v_fmac_f32_e32 v65, v62, v65
	v_div_scale_f32 v62, vcc, v63, v3, v63
	v_mul_f32_e32 v66, v62, v65
	v_fma_f32 v67, -v64, v66, v62
	v_fmac_f32_e32 v66, v67, v65
	v_fma_f32 v62, -v64, v66, v62
	v_div_fmas_f32 v62, v62, v65, v66
	v_div_fixup_f32 v3, v62, v3, v63
	v_bfe_u32 v62, v3, 16, 1
	v_add3_u32 v3, v3, v62, s85
	global_store_short_d16_hi v[60:61], v3, off
	s_waitcnt lgkmcnt(0)
	s_addc_u32 s31, s31, 0
	v_mov_b64_e32 v[62:63], v[54:55]
	s_cmp_eq_u32 s30, 0x200000
	v_mov_b64_e32 v[60:61], v[52:53]
	s_waitcnt vmcnt(4)
	v_mov_b32_e32 v64, v56
	v_mov_b32_e32 v65, v57
	v_mov_b32_e32 v66, v58
	v_mov_b32_e32 v67, v59
	v_mov_b32_e32 v117, v2
	v_mov_b32_e32 v118, v0
	s_cbranch_scc1 .LBB0_727
